# Up GEMM K-loop: the two As[0][0] LDS-DMA pieces moved from the 6-piece SP2 load segment to the following 2-piece SP1 segment (4+4 balance), SP2 wait vmcnt(8)->(6)
# baseline (speedup 1.0000x reference)
.LBB0_2348:
	s_add_u32 s0, s46, 0xfffc0080
	s_addc_u32 s1, s47, -1
	s_add_i32 s64, 0, 0x10000
	s_cmp_eq_u32 s71, 12
	s_cselect_b32 s3, s7, s1
	s_cselect_b32 s2, s15, s0
	s_cselect_b32 s1, s13, s62
	s_cselect_b32 s0, s50, s51
	s_add_i32 s76, 0, 0x14000
	v_add_u32_e32 v144, s64, v3
	v_add_u32_e32 v167, s76, v3
	ds_read_b128 v[132:135], v144
	ds_read_b128 v[136:139], v144 offset:1024
	ds_read_b128 v[140:143], v144 offset:2048
	ds_read_b128 v[144:147], v144 offset:3072
	ds_read_b128 v[158:161], v167
	ds_read_b128 v[162:165], v167 offset:1024
	ds_read_b128 v[168:171], v167 offset:2048
	ds_read_b128 v[172:175], v167 offset:3072
	v_lshl_add_u64 v[208:209], s[46:47], 0, v[154:155]
	s_add_i32 m0, s21, 0xc000
	ds_read_b128 v[176:179], v166
	ds_read_b128 v[180:183], v166 offset:1024
	ds_read_b128 v[184:187], v166 offset:2048
	ds_read_b128 v[188:191], v166 offset:3072
	ds_read_b128 v[192:195], v166 offset:4096
	ds_read_b128 v[196:199], v166 offset:5120
	ds_read_b128 v[200:203], v166 offset:6144
	ds_read_b128 v[204:207], v166 offset:7168
	global_load_lds_dwordx4 v[208:209], off
	v_lshl_add_u64 v[208:209], s[46:47], 0, v[156:157]
	s_add_i32 m0, s21, 0xe000
	s_nop 0
	global_load_lds_dwordx4 v[208:209], off
	s_waitcnt vmcnt(8)
	s_waitcnt lgkmcnt(0)
	s_barrier
	s_setprio 1
	s_waitcnt lgkmcnt(0)
	v_mfma_f32_16x16x32_bf16 v[128:131], v[132:135], v[176:179], v[128:131]
	v_mfma_f32_16x16x32_bf16 v[124:127], v[140:143], v[176:179], v[124:127]
	v_mfma_f32_16x16x32_bf16 v[112:115], v[132:135], v[184:187], v[112:115]
	v_mfma_f32_16x16x32_bf16 v[108:111], v[140:143], v[184:187], v[108:111]
	v_mfma_f32_16x16x32_bf16 v[96:99], v[132:135], v[192:195], v[96:99]
	v_mfma_f32_16x16x32_bf16 v[92:95], v[140:143], v[192:195], v[92:95]
	v_mfma_f32_16x16x32_bf16 v[80:83], v[132:135], v[200:203], v[80:83]
	v_mfma_f32_16x16x32_bf16 v[76:79], v[140:143], v[200:203], v[76:79]
	v_mfma_f32_16x16x32_bf16 v[128:131], v[136:139], v[180:183], v[128:131]
	v_mfma_f32_16x16x32_bf16 v[124:127], v[144:147], v[180:183], v[124:127]
	v_mfma_f32_16x16x32_bf16 v[112:115], v[136:139], v[188:191], v[112:115]
	v_mfma_f32_16x16x32_bf16 v[108:111], v[144:147], v[188:191], v[108:111]
	v_mfma_f32_16x16x32_bf16 v[96:99], v[136:139], v[196:199], v[96:99]
	v_mfma_f32_16x16x32_bf16 v[92:95], v[144:147], v[196:199], v[92:95]
	v_mfma_f32_16x16x32_bf16 v[80:83], v[136:139], v[204:207], v[80:83]
	v_mfma_f32_16x16x32_bf16 v[76:79], v[144:147], v[204:207], v[76:79]
	s_setprio 0
	s_setprio 1
	v_mfma_f32_16x16x32_bf16 v[120:123], v[158:161], v[176:179], v[120:123]
	v_mfma_f32_16x16x32_bf16 v[116:119], v[168:171], v[176:179], v[116:119]
	v_mfma_f32_16x16x32_bf16 v[104:107], v[158:161], v[184:187], v[104:107]
	v_mfma_f32_16x16x32_bf16 v[100:103], v[168:171], v[184:187], v[100:103]
	v_mfma_f32_16x16x32_bf16 v[88:91], v[158:161], v[192:195], v[88:91]
	v_mfma_f32_16x16x32_bf16 v[84:87], v[168:171], v[192:195], v[84:87]
	v_mfma_f32_16x16x32_bf16 v[72:75], v[158:161], v[200:203], v[72:75]
	v_mfma_f32_16x16x32_bf16 v[68:71], v[168:171], v[200:203], v[68:71]
	v_mfma_f32_16x16x32_bf16 v[120:123], v[162:165], v[180:183], v[120:123]
	v_mfma_f32_16x16x32_bf16 v[116:119], v[172:175], v[180:183], v[116:119]
	v_mfma_f32_16x16x32_bf16 v[104:107], v[162:165], v[188:191], v[104:107]
	v_mfma_f32_16x16x32_bf16 v[100:103], v[172:175], v[188:191], v[100:103]
	v_mfma_f32_16x16x32_bf16 v[88:91], v[162:165], v[196:199], v[88:91]
	v_mfma_f32_16x16x32_bf16 v[84:87], v[172:175], v[196:199], v[84:87]
	v_mfma_f32_16x16x32_bf16 v[72:75], v[162:165], v[204:207], v[72:75]
	v_mfma_f32_16x16x32_bf16 v[68:71], v[172:175], v[204:207], v[68:71]
	s_setprio 0
	s_barrier
	s_add_i32 s64, s64, s29
	v_lshl_add_u64 v[208:209], s[0:1], 0, v[148:149]
	s_mov_b32 m0, s64
	ds_read_b128 v[176:179], v166 offset:16384
	ds_read_b128 v[180:183], v166 offset:17408
	ds_read_b128 v[184:187], v166 offset:18432
	ds_read_b128 v[188:191], v166 offset:19456
	ds_read_b128 v[192:195], v166 offset:20480
	ds_read_b128 v[196:199], v166 offset:21504
	ds_read_b128 v[200:203], v166 offset:22528
	ds_read_b128 v[204:207], v166 offset:23552
	global_load_lds_dwordx4 v[208:209], off
	s_add_i32 m0, s64, 0x2000
	s_add_u32 s64, s0, 0x4000
	v_lshl_add_u64 v[210:211], s[0:1], 0, v[152:153]
	s_addc_u32 s65, s1, 0
	s_add_i32 s76, s76, s29
	global_load_lds_dwordx4 v[210:211], off
	v_lshl_add_u64 v[212:213], s[64:65], 0, v[148:149]
	s_mov_b32 m0, s76
	v_lshl_add_u64 v[214:215], s[2:3], 0, v[150:151]
	global_load_lds_dwordx4 v[212:213], off
	v_lshl_add_u64 v[212:213], s[64:65], 0, v[152:153]
	s_add_i32 m0, s76, 0x2000
	s_nop 0
	global_load_lds_dwordx4 v[212:213], off
	v_lshl_add_u64 v[212:213], s[2:3], 0, v[0:1]
	s_waitcnt vmcnt(6)
	s_waitcnt lgkmcnt(0)
	s_barrier
	s_setprio 1
	s_waitcnt lgkmcnt(0)
	v_mfma_f32_16x16x32_bf16 v[64:67], v[132:135], v[176:179], v[64:67]
	v_mfma_f32_16x16x32_bf16 v[60:63], v[140:143], v[176:179], v[60:63]
	v_mfma_f32_16x16x32_bf16 v[48:51], v[132:135], v[184:187], v[48:51]
	v_mfma_f32_16x16x32_bf16 v[44:47], v[140:143], v[184:187], v[44:47]
	v_mfma_f32_16x16x32_bf16 v[32:35], v[132:135], v[192:195], v[32:35]
	v_mfma_f32_16x16x32_bf16 v[28:31], v[140:143], v[192:195], v[28:31]
	v_mfma_f32_16x16x32_bf16 v[16:19], v[132:135], v[200:203], v[16:19]
	v_mfma_f32_16x16x32_bf16 v[12:15], v[140:143], v[200:203], v[12:15]
	v_mfma_f32_16x16x32_bf16 v[64:67], v[136:139], v[180:183], v[64:67]
	v_mfma_f32_16x16x32_bf16 v[60:63], v[144:147], v[180:183], v[60:63]
	v_mfma_f32_16x16x32_bf16 v[48:51], v[136:139], v[188:191], v[48:51]
	v_mfma_f32_16x16x32_bf16 v[44:47], v[144:147], v[188:191], v[44:47]
	v_mfma_f32_16x16x32_bf16 v[32:35], v[136:139], v[196:199], v[32:35]
	v_mfma_f32_16x16x32_bf16 v[28:31], v[144:147], v[196:199], v[28:31]
	v_mfma_f32_16x16x32_bf16 v[16:19], v[136:139], v[204:207], v[16:19]
	v_mfma_f32_16x16x32_bf16 v[12:15], v[144:147], v[204:207], v[12:15]
	s_setprio 0
	s_setprio 1
	v_mfma_f32_16x16x32_bf16 v[56:59], v[158:161], v[176:179], v[56:59]
	v_mfma_f32_16x16x32_bf16 v[52:55], v[168:171], v[176:179], v[52:55]
	v_mfma_f32_16x16x32_bf16 v[40:43], v[158:161], v[184:187], v[40:43]
	v_mfma_f32_16x16x32_bf16 v[36:39], v[168:171], v[184:187], v[36:39]
	v_mfma_f32_16x16x32_bf16 v[24:27], v[158:161], v[192:195], v[24:27]
	v_mfma_f32_16x16x32_bf16 v[20:23], v[168:171], v[192:195], v[20:23]
	v_mfma_f32_16x16x32_bf16 v[8:11], v[158:161], v[200:203], v[8:11]
	v_mfma_f32_16x16x32_bf16 v[4:7], v[168:171], v[200:203], v[4:7]
	v_mfma_f32_16x16x32_bf16 v[56:59], v[162:165], v[180:183], v[56:59]
	v_mfma_f32_16x16x32_bf16 v[52:55], v[172:175], v[180:183], v[52:55]
	v_mfma_f32_16x16x32_bf16 v[40:43], v[162:165], v[188:191], v[40:43]
	v_mfma_f32_16x16x32_bf16 v[36:39], v[172:175], v[188:191], v[36:39]
	v_mfma_f32_16x16x32_bf16 v[24:27], v[162:165], v[196:199], v[24:27]
	v_mfma_f32_16x16x32_bf16 v[20:23], v[172:175], v[196:199], v[20:23]
	v_mfma_f32_16x16x32_bf16 v[8:11], v[162:165], v[204:207], v[8:11]
	v_mfma_f32_16x16x32_bf16 v[4:7], v[172:175], v[204:207], v[4:7]
	s_setprio 0
	s_barrier
	s_add_i32 s64, 0, 0x18000
	s_add_i32 s65, 0, 0x1c000
	v_add_u32_e32 v144, s64, v3
	v_add_u32_e32 v167, s65, v3
	ds_read_b128 v[132:135], v144
	ds_read_b128 v[136:139], v144 offset:1024
	ds_read_b128 v[140:143], v144 offset:2048
	ds_read_b128 v[144:147], v144 offset:3072
	ds_read_b128 v[158:161], v167
	ds_read_b128 v[162:165], v167 offset:1024
	ds_read_b128 v[168:171], v167 offset:2048
	ds_read_b128 v[172:175], v167 offset:3072
	s_mov_b32 m0, s21
	s_nop 0
	global_load_lds_dwordx4 v[212:213], off
	s_mov_b32 m0, s30
	s_nop 0
	global_load_lds_dwordx4 v[214:215], off
	s_add_u32 s2, s2, 0x40000
	s_addc_u32 s3, s3, 0
	s_mov_b32 m0, s31
	v_lshl_add_u64 v[216:217], s[2:3], 0, v[0:1]
	ds_read_b128 v[176:179], v166 offset:32768
	ds_read_b128 v[180:183], v166 offset:33792
	ds_read_b128 v[184:187], v166 offset:34816
	ds_read_b128 v[188:191], v166 offset:35840
	ds_read_b128 v[192:195], v166 offset:36864
	ds_read_b128 v[196:199], v166 offset:37888
	ds_read_b128 v[200:203], v166 offset:38912
	ds_read_b128 v[204:207], v166 offset:39936
	global_load_lds_dwordx4 v[216:217], off
	v_lshl_add_u64 v[216:217], s[2:3], 0, v[150:151]
	s_mov_b32 m0, s52
	s_nop 0
	global_load_lds_dwordx4 v[216:217], off
	s_waitcnt vmcnt(8)
	s_waitcnt lgkmcnt(0)
	s_barrier
	s_setprio 1
	s_waitcnt lgkmcnt(0)
	v_mfma_f32_16x16x32_bf16 v[128:131], v[132:135], v[176:179], v[128:131]
	v_mfma_f32_16x16x32_bf16 v[124:127], v[140:143], v[176:179], v[124:127]
	v_mfma_f32_16x16x32_bf16 v[112:115], v[132:135], v[184:187], v[112:115]
	v_mfma_f32_16x16x32_bf16 v[108:111], v[140:143], v[184:187], v[108:111]
	v_mfma_f32_16x16x32_bf16 v[96:99], v[132:135], v[192:195], v[96:99]
	v_mfma_f32_16x16x32_bf16 v[92:95], v[140:143], v[192:195], v[92:95]
	v_mfma_f32_16x16x32_bf16 v[80:83], v[132:135], v[200:203], v[80:83]
	v_mfma_f32_16x16x32_bf16 v[76:79], v[140:143], v[200:203], v[76:79]
	v_mfma_f32_16x16x32_bf16 v[128:131], v[136:139], v[180:183], v[128:131]
	v_mfma_f32_16x16x32_bf16 v[124:127], v[144:147], v[180:183], v[124:127]
	v_mfma_f32_16x16x32_bf16 v[112:115], v[136:139], v[188:191], v[112:115]
	v_mfma_f32_16x16x32_bf16 v[108:111], v[144:147], v[188:191], v[108:111]
	v_mfma_f32_16x16x32_bf16 v[96:99], v[136:139], v[196:199], v[96:99]
	v_mfma_f32_16x16x32_bf16 v[92:95], v[144:147], v[196:199], v[92:95]
	v_mfma_f32_16x16x32_bf16 v[80:83], v[136:139], v[204:207], v[80:83]
	v_mfma_f32_16x16x32_bf16 v[76:79], v[144:147], v[204:207], v[76:79]
	s_setprio 0
	s_setprio 1
	v_mfma_f32_16x16x32_bf16 v[120:123], v[158:161], v[176:179], v[120:123]
	v_mfma_f32_16x16x32_bf16 v[116:119], v[168:171], v[176:179], v[116:119]
	v_mfma_f32_16x16x32_bf16 v[104:107], v[158:161], v[184:187], v[104:107]
	v_mfma_f32_16x16x32_bf16 v[100:103], v[168:171], v[184:187], v[100:103]
	v_mfma_f32_16x16x32_bf16 v[88:91], v[158:161], v[192:195], v[88:91]
	v_mfma_f32_16x16x32_bf16 v[84:87], v[168:171], v[192:195], v[84:87]
	v_mfma_f32_16x16x32_bf16 v[72:75], v[158:161], v[200:203], v[72:75]
	v_mfma_f32_16x16x32_bf16 v[68:71], v[168:171], v[200:203], v[68:71]
	v_mfma_f32_16x16x32_bf16 v[120:123], v[162:165], v[180:183], v[120:123]
	v_mfma_f32_16x16x32_bf16 v[116:119], v[172:175], v[180:183], v[116:119]
	v_mfma_f32_16x16x32_bf16 v[104:107], v[162:165], v[188:191], v[104:107]
	v_mfma_f32_16x16x32_bf16 v[100:103], v[172:175], v[188:191], v[100:103]
	v_mfma_f32_16x16x32_bf16 v[88:91], v[162:165], v[196:199], v[88:91]
	v_mfma_f32_16x16x32_bf16 v[84:87], v[172:175], v[196:199], v[84:87]
	v_mfma_f32_16x16x32_bf16 v[72:75], v[162:165], v[204:207], v[72:75]
	v_mfma_f32_16x16x32_bf16 v[68:71], v[172:175], v[204:207], v[68:71]
	s_setprio 0
	s_barrier
	s_add_i32 s2, s64, s29
	v_lshl_add_u64 v[208:209], v[208:209], 0, s[60:61]
	s_mov_b32 m0, s2
	ds_read_b128 v[176:179], v166 offset:49152
	ds_read_b128 v[180:183], v166 offset:50176
	ds_read_b128 v[184:187], v166 offset:51200
	ds_read_b128 v[188:191], v166 offset:52224
	ds_read_b128 v[192:195], v166 offset:53248
	ds_read_b128 v[196:199], v166 offset:54272
	ds_read_b128 v[200:203], v166 offset:55296
	ds_read_b128 v[204:207], v166 offset:56320
	global_load_lds_dwordx4 v[208:209], off
	s_add_i32 m0, s2, 0x2000
	s_add_u32 s0, s0, 0x4080
	v_lshl_add_u64 v[208:209], v[210:211], 0, s[60:61]
	s_addc_u32 s1, s1, 0
	s_add_i32 s2, s65, s29
	global_load_lds_dwordx4 v[208:209], off
	v_lshl_add_u64 v[208:209], s[0:1], 0, v[148:149]
	s_mov_b32 m0, s2
	s_nop 0
	global_load_lds_dwordx4 v[208:209], off
	v_lshl_add_u64 v[208:209], s[0:1], 0, v[152:153]
	s_add_i32 m0, s2, 0x2000
	s_nop 0
	global_load_lds_dwordx4 v[208:209], off
	v_lshl_add_u64 v[208:209], v[212:213], 0, s[60:61]
	s_mov_b32 m0, s56
	s_nop 0
	global_load_lds_dwordx4 v[208:209], off
	v_lshl_add_u64 v[208:209], v[214:215], 0, s[60:61]
	s_mov_b32 m0, s57
	s_nop 0
	global_load_lds_dwordx4 v[208:209], off
	s_waitcnt vmcnt(8)
	s_waitcnt lgkmcnt(0)
	s_barrier
	s_setprio 1
	s_waitcnt lgkmcnt(0)
	v_mfma_f32_16x16x32_bf16 v[64:67], v[132:135], v[176:179], v[64:67]
	v_mfma_f32_16x16x32_bf16 v[60:63], v[140:143], v[176:179], v[60:63]
	v_mfma_f32_16x16x32_bf16 v[48:51], v[132:135], v[184:187], v[48:51]
	v_mfma_f32_16x16x32_bf16 v[44:47], v[140:143], v[184:187], v[44:47]
	v_mfma_f32_16x16x32_bf16 v[32:35], v[132:135], v[192:195], v[32:35]
	v_mfma_f32_16x16x32_bf16 v[28:31], v[140:143], v[192:195], v[28:31]
	v_mfma_f32_16x16x32_bf16 v[16:19], v[132:135], v[200:203], v[16:19]
	v_mfma_f32_16x16x32_bf16 v[12:15], v[140:143], v[200:203], v[12:15]
	v_mfma_f32_16x16x32_bf16 v[64:67], v[136:139], v[180:183], v[64:67]
	v_mfma_f32_16x16x32_bf16 v[60:63], v[144:147], v[180:183], v[60:63]
	v_mfma_f32_16x16x32_bf16 v[48:51], v[136:139], v[188:191], v[48:51]
	v_mfma_f32_16x16x32_bf16 v[44:47], v[144:147], v[188:191], v[44:47]
	v_mfma_f32_16x16x32_bf16 v[32:35], v[136:139], v[196:199], v[32:35]
	v_mfma_f32_16x16x32_bf16 v[28:31], v[144:147], v[196:199], v[28:31]
	v_mfma_f32_16x16x32_bf16 v[16:19], v[136:139], v[204:207], v[16:19]
	v_mfma_f32_16x16x32_bf16 v[12:15], v[144:147], v[204:207], v[12:15]
	s_setprio 0
	s_setprio 1
	v_mfma_f32_16x16x32_bf16 v[56:59], v[158:161], v[176:179], v[56:59]
	v_mfma_f32_16x16x32_bf16 v[52:55], v[168:171], v[176:179], v[52:55]
	v_mfma_f32_16x16x32_bf16 v[40:43], v[158:161], v[184:187], v[40:43]
	v_mfma_f32_16x16x32_bf16 v[36:39], v[168:171], v[184:187], v[36:39]
	v_mfma_f32_16x16x32_bf16 v[24:27], v[158:161], v[192:195], v[24:27]
	v_mfma_f32_16x16x32_bf16 v[20:23], v[168:171], v[192:195], v[20:23]
	v_mfma_f32_16x16x32_bf16 v[8:11], v[158:161], v[200:203], v[8:11]
	v_mfma_f32_16x16x32_bf16 v[4:7], v[168:171], v[200:203], v[4:7]
	v_mfma_f32_16x16x32_bf16 v[56:59], v[162:165], v[180:183], v[56:59]
	v_mfma_f32_16x16x32_bf16 v[52:55], v[172:175], v[180:183], v[52:55]
	v_mfma_f32_16x16x32_bf16 v[40:43], v[162:165], v[188:191], v[40:43]
	v_mfma_f32_16x16x32_bf16 v[36:39], v[172:175], v[188:191], v[36:39]
	v_mfma_f32_16x16x32_bf16 v[24:27], v[162:165], v[196:199], v[24:27]
	v_mfma_f32_16x16x32_bf16 v[20:23], v[172:175], v[196:199], v[20:23]
	v_mfma_f32_16x16x32_bf16 v[8:11], v[162:165], v[204:207], v[8:11]
	v_mfma_f32_16x16x32_bf16 v[4:7], v[172:175], v[204:207], v[4:7]
	s_setprio 0
	s_barrier
	s_add_i32 s71, s71, 2
	s_add_u32 s46, s46, 0x100
	s_addc_u32 s47, s47, 0
	s_add_u32 s51, s51, 0x100
	s_addc_u32 s62, s62, 0
	s_cmp_gt_u32 s71, 13
	s_cbranch_scc0 .LBB0_2348
	s_and_b64 vcc, exec, s[10:11]
	s_cbranch_vccz .LBB0_2351
	s_barrier
